# in-proj WGM 4 on top of best
# speedup vs baseline: 1.0034x; 1.0011x over previous
;     __host__ __device__ bool next(int i, Unit& u) const {
;         const long L = (long)i * G + c; if (L >= nwg) return false;
;         int wgid = (int)L; { const int q = nwg / NXCD, r = nwg % NXCD, xcd = wgid % NXCD, off = wgid / NXCD; wgid = (xcd < r ? xcd * (q + 1) : r * (q + 1) + (xcd - r) * q) + off; }
;         const int nig = WGM * nN, gid = wgid / nig, fm = gid * WGM, gsz = (nM - fm) < WGM ? (nM - fm) : WGM;
;         u.pm = fm + ((wgid % nig) % gsz); u.pn = (wgid % nig) / gsz; return true;
;     }
; __global__ void __launch_bounds__(512, 2) fwd_kernel(Args a_unused) {
;     ...
;         if (sp == 0 && (PHM & 2)) {
;             pg8::Gemm g{XB, (const bf16_t*)(ws + WS_WIN + l * SZ_WIN), SEQ, NINP, DM, DM}; pg8::StaticOrder S; S.init(SEQ, NINP, G, (int)blockIdx.x);
;             pg8::EpiScaleBf16<false> E{PROJ, NINP, SSQ + (2 * l) * SEQ};
;             pg8::gemm_phase<pg8::EpiScaleBf16<false>, pg8::StaticOrder, true, true>(lds, g, S, E);
;             if ((int)blockIdx.x >= (SEQ / 256) * (NINP / 256) - 2 * G) tr_drain(a, lds, tid_, (int*)(ws + WS_CNT) + 24 + 2 * l, l, 1, 1);
;         } else if (sp == 1 && (PHM & 4)) {
;             for (int m = gw; m < SEQ; m += NGW) post_proj_row(a, l, m, lane);
;         } else if (sp == 2 && (PHM & 8)) {
;             if ((int)blockIdx.x < 6) fox_cumsum(a, (int)blockIdx.x, lds);
;             { pg8::Gemm g{PROJ + C_MQ, (const bf16_t*)(ws + WS_WQUP + l * SZ_WQUP), SEQ, NQUPP, 512, NINP}; pg8::StaticOrder S; S.init(SEQ, NQUPP, G, (int)blockIdx.x);
;               pg8::EpiScaleBf16<false> E{QC, NQUPP, nullptr};
;               pg8::gemm_phase<pg8::EpiScaleBf16<false>, pg8::StaticOrder, true, true>(lds, g, S, E); }
;             { pg8::Gemm g{PROJ + C_CKV, (const bf16_t*)(ws + WS_WKVUP + l * SZ_WKVUP), SEQ, NKVUP, 256, NINP}; pg8::StaticOrder S; if (G == 256) S.init(SEQ, NKVUP, 96, (int)blockIdx.x >= 160 ? (int)blockIdx.x - 160 : 192); else S.init(SEQ, NKVUP, G, (int)((blockIdx.x + 128) % G));
;               pg8::EpiScaleBf16<false> E{KVC, NKVUP, nullptr};
;               pg8::gemm_phase<pg8::EpiScaleBf16<false>, pg8::StaticOrder, true, true>(lds, g, S, E); }
;         } else if (sp == 3 && (PHM & 16)) {
;             for (int m = gw; m < SEQ; m += NGW) post_mla_row(a, l, m, lane);
;         } else if (sp == 4 && (PHM & 32)) {
;             attention_phase<0>(a, l, lds, 0);
.LBB0_274:
	s_waitcnt lgkmcnt(0)
	s_lshr_b32 s0, s16, 16
	v_writelane_b32 v254, s0, 7
	s_and_b32 s0, s16, 0xffff
	s_lshl_b32 s2, s82, 3
	s_lshl_b32 s73, s22, 3
	s_cmpk_lt_i32 s82, 0x100
	s_cselect_b64 s[4:5], -1, 0
	s_ashr_i32 s84, s82, 31
	v_writelane_b32 v254, s2, 8
	s_lshr_b32 s2, s84, 29
	s_add_i32 s2, s82, s2
	s_ashr_i32 s6, s2, 3
	s_and_b32 s2, s2, -8
	s_sub_i32 s7, s82, s2
	s_mul_i32 s1, s23, s22
	s_lshl_b32 s2, s7, 5
	s_ashr_i32 s23, s22, 31
	v_writelane_b32 v254, s4, 9
	s_cmpk_lt_i32 s82, 0x400
	v_bfe_u32 v1, v0, 10, 10
	v_writelane_b32 v254, s5, 10
	s_cselect_b64 s[4:5], -1, 0
	v_writelane_b32 v254, s4, 11
	v_bfe_u32 v0, v0, 20, 10
	v_mad_u32_u24 v197, v0, s0, v1
	v_writelane_b32 v254, s5, 12
	s_lshl_b32 s4, s7, 7
	s_lshl_b32 s5, s0, 8
	s_cmp_lt_i32 s82, 6
	v_writelane_b32 v254, s5, 13
	s_cselect_b64 s[8:9], -1, 0
	v_writelane_b32 v254, s8, 14
	s_cmpk_lt_i32 s82, 0xa0
	s_mul_i32 s57, s1, s3
	v_writelane_b32 v254, s9, 15
	s_cselect_b64 s[8:9], -1, 0
	v_writelane_b32 v254, s8, 16
	s_cmpk_lg_i32 s22, 0x100
	v_cvt_f32_u32_e32 v0, s22
	v_writelane_b32 v254, s9, 17
	s_cselect_b64 s[8:9], -1, 0
	v_writelane_b32 v254, s8, 18
	s_add_i32 s5, s82, 0xffffff60
	v_rcp_iflag_f32_e32 v0, v0
	v_writelane_b32 v254, s9, 19
	s_add_i32 s8, s82, 0x80
	s_cmpk_gt_i32 s82, 0x9f
	s_cselect_b32 s5, s5, 0xc0
	s_cmpk_lt_i32 s82, 0x260
	v_writelane_b32 v254, s5, 20
	s_cselect_b64 s[10:11], -1, 0
	s_lshl_b32 s5, s22, 1
	s_sub_i32 s5, 0x260, s5
	v_writelane_b32 v254, s10, 21
	s_cmp_ge_i32 s82, s5
	s_mul_i32 s5, s7, 33
	v_writelane_b32 v254, s11, 22
	s_cselect_b64 s[10:11], -1, 0
	s_cmp_lt_i32 s7, 0
	s_mul_i32 s9, s7, 0x81
	s_cselect_b32 s0, s5, s2
	s_movk_i32 s2, 0x4d
	s_cselect_b32 s1, s9, s4
	s_cselect_b32 s3, 21, 20
	s_cselect_b32 s9, s2, 0x4c
	s_add_i32 s0, s0, s6
	s_ashr_i32 s2, s0, 31
	s_lshr_b32 s2, s2, 28
	s_add_i32 s2, s0, s2
	s_ashr_i32 s4, s2, 4
	s_and_b32 s2, s2, 0xfff0
	s_sub_i32 s2, s0, s2
	s_bfe_u32 s0, s2, 0x10007
	s_add_i32 s5, s2, s0
	s_bfe_i32 s0, s5, 0x80000
	s_and_b32 s5, s5, 0xfe
	v_writelane_b32 v254, s10, 23
	s_sub_i32 s2, s2, s5
	s_lshl_b32 s4, s4, 1
	v_writelane_b32 v254, s11, 24
	s_sext_i32_i16 s10, s0
	s_sext_i32_i8 s2, s2
	s_add_i32 s12, s4, s2
	s_ashr_i32 s2, s10, 1
	s_add_i32 s1, s1, s6
	v_writelane_b32 v254, s2, 25
	s_ashr_i32 s2, s1, 31
	s_lshr_b32 s2, s2, 25
	s_add_i32 s2, s1, s2
	s_ashr_i32 s4, s2, 7
	s_and_b32 s2, s2, 0xff80
	s_sub_i32 s1, s1, s2
	s_bfe_u32 s2, s1, 0x10007
	s_add_i32 s5, s1, s2
	s_bfe_i32 s2, s5, 0x80000
	s_and_b32 s5, s5, 0xfc
	s_sub_i32 s1, s1, s5
	s_lshr_b32 s0, s10, 1
	s_lshl_b32 s4, s4, 2
	s_sext_i32_i16 s10, s2
	s_sext_i32_i8 s1, s1
	s_mul_i32 s3, s7, s3
	s_add_i32 s14, s4, s1
	s_ashr_i32 s1, s10, 2
	s_add_i32 s3, s3, s6
	v_writelane_b32 v254, s1, 26
	s_mul_hi_i32 s1, s3, 0x66666667
	s_lshr_b32 s4, s1, 31
	s_ashr_i32 s1, s1, 2
	s_add_i32 s1, s1, s4
	s_mul_i32 s4, s1, 10
	s_sub_i32 s3, s3, s4
	s_bfe_u32 s4, s3, 0x10007
	s_add_i32 s5, s3, s4
	s_bfe_i32 s4, s5, 0x80000
	s_and_b32 s5, s5, 0xfe
	s_sub_i32 s3, s3, s5
	s_lshl_b32 s1, s1, 1
	s_sext_i32_i8 s3, s3
	s_lshr_b32 s2, s10, 2
	s_sext_i32_i16 s10, s4
	s_add_i32 s1, s1, s3
	s_lshr_b32 s4, s10, 1
	v_writelane_b32 v254, s1, 27
	s_ashr_i32 s1, s10, 1
	v_writelane_b32 v254, s1, 28
	s_bfe_i64 s[4:5], s[4:5], 0x100000
	s_mul_i32 s1, s7, s9
	s_lshl_b64 s[4:5], s[4:5], 18
	s_add_i32 s1, s1, s6
	v_writelane_b32 v254, s4, 29
	s_mul_hi_i32 s3, s1, 0x6bca1af3
	s_ashr_i32 s13, s12, 31
	v_writelane_b32 v254, s5, 30
	s_lshr_b32 s4, s3, 31
	s_ashr_i32 s3, s3, 4
	s_add_i32 s3, s3, s4
	s_lshr_b32 s3, s3, 1
	s_lshl_b32 s5, s3, 2
	s_mul_i32 s3, s3, 0x4c
	s_sub_i32 s1, s1, s3
	s_bfe_u32 s3, s1, 0x10007
	s_add_i32 s3, s1, s3
	s_bfe_i32 s4, s3, 0x80000
	s_and_b32 s3, s3, 0xfc
	s_sub_i32 s1, s1, s3
	s_sext_i32_i16 s6, s4
;     __host__ __device__ bool next(int i, Unit& u) const {
;         const long L = (long)i * G + c; if (L >= nwg) return false;
;         int wgid = (int)L; { const int q = nwg / NXCD, r = nwg % NXCD, xcd = wgid % NXCD, off = wgid / NXCD; wgid = (xcd < r ? xcd * (q + 1) : r * (q + 1) + (xcd - r) * q) + off; }
;         const int nig = WGM * nN, gid = wgid / nig, fm = gid * WGM, gsz = (nM - fm) < WGM ? (nM - fm) : WGM;
;         u.pm = fm + ((wgid % nig) % gsz); u.pn = (wgid % nig) / gsz; return true;
;     }
; __global__ void __launch_bounds__(512, 2) fwd_kernel(Args a_unused) {
;     ...
;         if (sp == 0 && (PHM & 2)) {
;             pg8::Gemm g{XB, (const bf16_t*)(ws + WS_WIN + l * SZ_WIN), SEQ, NINP, DM, DM}; pg8::StaticOrder S; S.init(SEQ, NINP, G, (int)blockIdx.x);
;             pg8::EpiScaleBf16<false> E{PROJ, NINP, SSQ + (2 * l) * SEQ};
;             pg8::gemm_phase<pg8::EpiScaleBf16<false>, pg8::StaticOrder, true, true>(lds, g, S, E);
;             if ((int)blockIdx.x >= (SEQ / 256) * (NINP / 256) - 2 * G) tr_drain(a, lds, tid_, (int*)(ws + WS_CNT) + 24 + 2 * l, l, 1, 1);
;         } else if (sp == 1 && (PHM & 4)) {
;             for (int m = gw; m < SEQ; m += NGW) post_proj_row(a, l, m, lane);
;         } else if (sp == 2 && (PHM & 8)) {
;             if ((int)blockIdx.x < 6) fox_cumsum(a, (int)blockIdx.x, lds);
;             { pg8::Gemm g{PROJ + C_MQ, (const bf16_t*)(ws + WS_WQUP + l * SZ_WQUP), SEQ, NQUPP, 512, NINP}; pg8::StaticOrder S; S.init(SEQ, NQUPP, G, (int)blockIdx.x);
;               pg8::EpiScaleBf16<false> E{QC, NQUPP, nullptr};
;               pg8::gemm_phase<pg8::EpiScaleBf16<false>, pg8::StaticOrder, true, true>(lds, g, S, E); }
;             { pg8::Gemm g{PROJ + C_CKV, (const bf16_t*)(ws + WS_WKVUP + l * SZ_WKVUP), SEQ, NKVUP, 256, NINP}; pg8::StaticOrder S; if (G == 256) S.init(SEQ, NKVUP, 96, (int)blockIdx.x >= 160 ? (int)blockIdx.x - 160 : 192); else S.init(SEQ, NKVUP, G, (int)((blockIdx.x + 128) % G));
;               pg8::EpiScaleBf16<false> E{KVC, NKVUP, nullptr};
;               pg8::gemm_phase<pg8::EpiScaleBf16<false>, pg8::StaticOrder, true, true>(lds, g, S, E); }
;         } else if (sp == 3 && (PHM & 16)) {
;             for (int m = gw; m < SEQ; m += NGW) post_mla_row(a, l, m, lane);
;         } else if (sp == 4 && (PHM & 32)) {
;             attention_phase<0>(a, l, lds, 0);
	s_sext_i32_i8 s1, s1
	s_add_i32 s10, s5, s1
	s_ashr_i32 s1, s6, 2
	s_lshr_b32 s4, s6, 2
	v_writelane_b32 v254, s1, 31
	s_lshl_b64 s[6:7], s[12:13], 22
	v_writelane_b32 v254, s6, 32
	s_bfe_i64 s[0:1], s[0:1], 0x100000
	s_ashr_i32 s15, s14, 31
	v_writelane_b32 v254, s7, 33
	s_lshl_b64 s[6:7], s[0:1], 22
	v_writelane_b32 v254, s6, 34
	s_bfe_i64 s[2:3], s[2:3], 0x100000
	s_lshl_b64 s[2:3], s[2:3], 20
	v_writelane_b32 v254, s7, 35
	s_mov_b32 s6, s14
	v_writelane_b32 v254, s6, 36
	s_lshl_b64 s[0:1], s[0:1], 20
	s_ashr_i32 s11, s10, 31
	v_writelane_b32 v254, s7, 37
	s_lshl_b64 s[6:7], s[14:15], 20
	v_writelane_b32 v254, s6, 38
	v_mul_f32_e32 v0, 0x4f7ffffe, v0
	v_cvt_u32_f32_e32 v0, v0
	v_writelane_b32 v254, s7, 39
	v_writelane_b32 v254, s2, 40
	s_movk_i32 s89, 0xc00
	s_movk_i32 s81, 0x2600
	v_writelane_b32 v254, s3, 41
	s_mov_b32 s2, s12
	v_writelane_b32 v254, s2, 42
	s_mov_b32 s17, 0x10000
	v_mov_b32_e32 v1, 0
	v_writelane_b32 v254, s3, 43
	s_lshl_b64 s[2:3], s[12:13], 20
	v_writelane_b32 v254, s2, 44
	s_mov_b32 s24, 0x14000
	s_movk_i32 s86, 0x4000
	v_writelane_b32 v254, s3, 45
	v_writelane_b32 v254, s0, 46
	s_movk_i32 s3, 0xa00
	s_movk_i32 s93, 0x60
	v_writelane_b32 v254, s1, 47
	s_mov_b32 s0, s10
	v_writelane_b32 v254, s0, 48
	s_mov_b32 s87, 0x18000
	s_mov_b32 s74, 0x8000
	v_writelane_b32 v254, s1, 49
	s_lshl_b64 s[0:1], s[10:11], 20
	v_writelane_b32 v254, s0, 50
	s_mov_b32 s69, 0x1c000
	s_mov_b32 s78, 0xc000
	v_writelane_b32 v254, s1, 51
	s_bfe_i64 s[0:1], s[4:5], 0x100000
	s_lshl_b64 s[0:1], s[0:1], 20
	v_writelane_b32 v254, s0, 52
	v_mov_b32_e32 v198, 0x358637bd
	s_mov_b32 s16, 0x800000
	v_writelane_b32 v254, s1, 53
	s_sub_i32 s0, 0, s22
	v_readfirstlane_b32 s1, v0
	s_mul_i32 s0, s0, s1
	s_mul_hi_u32 s0, s1, s0
	s_add_i32 s1, s1, s0
	s_mul_hi_u32 s0, s8, s1
	s_mul_i32 s0, s0, s22
	s_sub_i32 s0, s8, s0
	s_sub_i32 s1, s0, s22
	s_cmp_ge_u32 s0, s22
	s_cselect_b32 s0, s1, s0
	s_sub_i32 s1, s0, s22
	s_cmp_ge_u32 s0, s22
	s_cselect_b32 s0, s1, s0
	v_writelane_b32 v254, s0, 54
	s_mul_i32 s0, s22, 0x6000
	s_mul_hi_i32 s1, s73, 0xc00
	v_writelane_b32 v254, s0, 55
	v_mov_b32_e32 v199, 0x2000
	v_mbcnt_lo_u32_b32 v0, -1, 0
	v_writelane_b32 v254, s1, 56
	s_mul_i32 s0, s22, 0x5000
	s_mul_hi_i32 s1, s73, 0xa00
	v_writelane_b32 v254, s0, 57
	v_mov_b32_e32 v216, 1
	v_mov_b64_e32 v[200:201], 0x100
	v_writelane_b32 v254, s1, 58
	s_lshl_b32 s0, s82, 8
	v_writelane_b32 v254, s0, 59
	s_lshl_b32 s0, s22, 8
	v_writelane_b32 v254, s0, 60
	s_mul_i32 s0, s22, 0x13000
	v_writelane_b32 v254, s0, 61
	s_lshl_b32 s0, s82, 6
	v_writelane_b32 v254, s0, 62
	s_lshl_b32 s0, s22, 6
	v_writelane_b32 v254, s0, 63
	s_mov_b32 s0, 0x20fc0
	s_add_i32 s88, s0, 0x100
	s_mov_b32 s0, 0x20080
	s_addk_i32 s0, 0x100
	v_writelane_b32 v255, s0, 0
	s_mov_b32 s0, 0x20084
	s_addk_i32 s0, 0x100
	v_writelane_b32 v255, s0, 1
	v_writelane_b32 v255, s73, 2
	v_writelane_b32 v255, s84, 3
	v_mov_b64_e32 v[202:203], 0xff
	v_mbcnt_hi_u32_b32 v217, -1, v0
	v_mov_b32_e32 v218, 0x7f800000
	v_mov_b32_e32 v219, 0xff800000
	v_mov_b32_e32 v220, 0x840
	v_mov_b32_e32 v221, 0x1080
	v_mov_b32_e32 v253, 0x100
	v_bfrev_b32_e32 v226, 40
	v_mov_b32_e32 v204, 0x3f317218
	v_mov_b64_e32 v[206:207], 0x260
	v_mov_b64_e32 v[208:209], 0x25f
	s_mov_b32 s79, 0x2aaaaaab
	s_mov_b32 s75, 0x41000000
	s_mov_b32 s83, 0x30000
	s_mov_b32 s68, 0x60000
	s_mov_b32 s70, 0x20000
	s_mov_b32 s72, 0x24000
	s_mov_b32 s60, 0x2c000
	s_mov_b32 s91, 0x6c000
	s_mov_b32 s56, 0x70000
	s_movk_i32 s71, 0x1246
	s_movk_i32 s54, 0x4918
	s_movk_i32 s25, 0xf05
	s_movk_i32 s55, 0xeff
	s_mov_b64 s[94:95], 0x80
	s_mov_b64 s[96:97], 0x100
	s_mov_b32 s80, 1.0
	s_mov_b32 s92, 0x3e0293ee
	s_mov_b32 s90, 1.0
	s_mov_b32 s34, 0x3b000000
	s_mov_b32 s37, 0
	v_writelane_b32 v255, s57, 4
	s_branch .LBB0_278
